# c15 + DIFF PV group-1 V fragments into loop-dead VGPRs so all 32 exps sit in MFMA gaps (2 per gap)
# speedup vs baseline: 1.0208x; 1.0208x over previous
.Lf_odd_exp:
	ds_read_b64_tr_b16 v[198:199], v1 offset:0x200
	ds_read_b64_tr_b16 v[200:201], v1 offset:0xa00
	ds_read_b64_tr_b16 v[230:231], v1 offset:0x1200
	ds_read_b64_tr_b16 v[232:233], v1 offset:0x1a00
	ds_read_b64_tr_b16 v[234:235], v1 offset:0x2200
	ds_read_b64_tr_b16 v[236:237], v1 offset:0x2a00
	ds_read_b64_tr_b16 v[238:239], v1 offset:0x3200
	ds_read_b64_tr_b16 v[240:241], v1 offset:0x3a00
	s_waitcnt lgkmcnt(8)
	v_mfma_f32_32x32x16_bf16 v[64:79], v[166:169], v[182:185], v[64:79]
	v_exp_f32_e32 v96, v128
	v_exp_f32_e32 v97, v129
	v_mfma_f32_32x32x16_bf16 v[64:79], v[12:15], v[178:181], v[64:79]
	v_exp_f32_e32 v98, v130
	v_exp_f32_e32 v99, v131
	v_mfma_f32_32x32x16_bf16 v[64:79], v[8:11], v[174:177], v[64:79]
	v_exp_f32_e32 v100, v132
	v_exp_f32_e32 v101, v133
	v_mfma_f32_32x32x16_bf16 v[64:79], v[4:7], v[170:173], v[64:79]
	v_exp_f32_e32 v102, v134
	v_exp_f32_e32 v103, v135
	ds_read_b64_tr_b16 v[182:183], v1 offset:0x400
	ds_read_b64_tr_b16 v[184:185], v1 offset:0xc00
	ds_read_b64_tr_b16 v[178:179], v1 offset:0x1400
	ds_read_b64_tr_b16 v[180:181], v1 offset:0x1c00
	ds_read_b64_tr_b16 v[174:175], v1 offset:0x2400
	ds_read_b64_tr_b16 v[176:177], v1 offset:0x2c00
	ds_read_b64_tr_b16 v[170:171], v1 offset:0x3400
	ds_read_b64_tr_b16 v[172:173], v1 offset:0x3c00
	s_waitcnt lgkmcnt(8)
	v_mfma_f32_32x32x16_bf16 v[48:63], v[166:169], v[198:201], v[48:63]
	v_exp_f32_e32 v104, v136
	v_exp_f32_e32 v105, v137
	v_mfma_f32_32x32x16_bf16 v[48:63], v[12:15], v[230:233], v[48:63]
	v_exp_f32_e32 v106, v138
	v_exp_f32_e32 v107, v139
	v_mfma_f32_32x32x16_bf16 v[48:63], v[8:11], v[234:237], v[48:63]
	v_exp_f32_e32 v108, v140
	v_exp_f32_e32 v109, v141
	v_mfma_f32_32x32x16_bf16 v[48:63], v[4:7], v[238:241], v[48:63]
	v_exp_f32_e32 v110, v142
	v_exp_f32_e32 v111, v143
	ds_read_b64_tr_b16 v[198:199], v1 offset:0x600
	ds_read_b64_tr_b16 v[200:201], v1 offset:0xe00
	ds_read_b64_tr_b16 v[230:231], v1 offset:0x1600
	ds_read_b64_tr_b16 v[232:233], v1 offset:0x1e00
	ds_read_b64_tr_b16 v[234:235], v1 offset:0x2600
	ds_read_b64_tr_b16 v[236:237], v1 offset:0x2e00
	ds_read_b64_tr_b16 v[238:239], v1 offset:0x3600
	ds_read_b64_tr_b16 v[240:241], v1 offset:0x3e00
	s_waitcnt lgkmcnt(8)
	v_mfma_f32_32x32x16_bf16 v[32:47], v[166:169], v[182:185], v[32:47]
	v_exp_f32_e32 v80, v112
	v_exp_f32_e32 v81, v113
	v_mfma_f32_32x32x16_bf16 v[32:47], v[12:15], v[178:181], v[32:47]
	v_exp_f32_e32 v82, v114
	v_exp_f32_e32 v83, v115
	v_mfma_f32_32x32x16_bf16 v[32:47], v[8:11], v[174:177], v[32:47]
	v_exp_f32_e32 v84, v116
	v_exp_f32_e32 v85, v117
	v_mfma_f32_32x32x16_bf16 v[32:47], v[4:7], v[170:173], v[32:47]
	v_exp_f32_e32 v86, v118
	v_exp_f32_e32 v87, v119
	s_waitcnt lgkmcnt(0)
	v_mfma_f32_32x32x16_bf16 v[16:31], v[166:169], v[198:201], v[16:31]
	v_exp_f32_e32 v88, v120
	v_exp_f32_e32 v89, v121
	v_mfma_f32_32x32x16_bf16 v[16:31], v[12:15], v[230:233], v[16:31]
	v_exp_f32_e32 v90, v122
	v_exp_f32_e32 v91, v123
	v_mfma_f32_32x32x16_bf16 v[16:31], v[8:11], v[234:237], v[16:31]
	v_exp_f32_e32 v92, v124
	v_exp_f32_e32 v93, v125
	v_mfma_f32_32x32x16_bf16 v[16:31], v[4:7], v[238:241], v[16:31]
	v_exp_f32_e32 v94, v126
	v_exp_f32_e32 v95, v127
	v_cmp_gt_f32_e32 vcc, 1.0, v225
	s_cbranch_vccnz .Lresc_odd_blk

.Lf_even_exp:
	ds_read_b64_tr_b16 v[198:199], v162 offset:0x200
	ds_read_b64_tr_b16 v[200:201], v162 offset:0xa00
	ds_read_b64_tr_b16 v[230:231], v162 offset:0x1200
	ds_read_b64_tr_b16 v[232:233], v162 offset:0x1a00
	ds_read_b64_tr_b16 v[234:235], v162 offset:0x2200
	ds_read_b64_tr_b16 v[236:237], v162 offset:0x2a00
	ds_read_b64_tr_b16 v[238:239], v162 offset:0x3200
	ds_read_b64_tr_b16 v[240:241], v162 offset:0x3a00
	s_waitcnt lgkmcnt(8)
	v_mfma_f32_32x32x16_bf16 v[64:79], v[166:169], v[182:185], v[64:79]
	v_exp_f32_e32 v96, v128
	v_exp_f32_e32 v97, v129
	v_mfma_f32_32x32x16_bf16 v[64:79], v[12:15], v[178:181], v[64:79]
	v_exp_f32_e32 v98, v130
	v_exp_f32_e32 v99, v131
	v_mfma_f32_32x32x16_bf16 v[64:79], v[8:11], v[174:177], v[64:79]
	v_exp_f32_e32 v100, v132
	v_exp_f32_e32 v101, v133
	v_mfma_f32_32x32x16_bf16 v[64:79], v[4:7], v[170:173], v[64:79]
	v_exp_f32_e32 v102, v134
	v_exp_f32_e32 v103, v135
	ds_read_b64_tr_b16 v[182:183], v162 offset:0x400
	ds_read_b64_tr_b16 v[184:185], v162 offset:0xc00
	ds_read_b64_tr_b16 v[178:179], v162 offset:0x1400
	ds_read_b64_tr_b16 v[180:181], v162 offset:0x1c00
	ds_read_b64_tr_b16 v[174:175], v162 offset:0x2400
	ds_read_b64_tr_b16 v[176:177], v162 offset:0x2c00
	ds_read_b64_tr_b16 v[170:171], v162 offset:0x3400
	ds_read_b64_tr_b16 v[172:173], v162 offset:0x3c00
	s_waitcnt lgkmcnt(8)
	v_mfma_f32_32x32x16_bf16 v[48:63], v[166:169], v[198:201], v[48:63]
	v_exp_f32_e32 v104, v136
	v_exp_f32_e32 v105, v137
	v_mfma_f32_32x32x16_bf16 v[48:63], v[12:15], v[230:233], v[48:63]
	v_exp_f32_e32 v106, v138
	v_exp_f32_e32 v107, v139
	v_mfma_f32_32x32x16_bf16 v[48:63], v[8:11], v[234:237], v[48:63]
	v_exp_f32_e32 v108, v140
	v_exp_f32_e32 v109, v141
	v_mfma_f32_32x32x16_bf16 v[48:63], v[4:7], v[238:241], v[48:63]
	v_exp_f32_e32 v110, v142
	v_exp_f32_e32 v111, v143
	ds_read_b64_tr_b16 v[198:199], v162 offset:0x600
	ds_read_b64_tr_b16 v[200:201], v162 offset:0xe00
	ds_read_b64_tr_b16 v[230:231], v162 offset:0x1600
	ds_read_b64_tr_b16 v[232:233], v162 offset:0x1e00
	ds_read_b64_tr_b16 v[234:235], v162 offset:0x2600
	ds_read_b64_tr_b16 v[236:237], v162 offset:0x2e00
	ds_read_b64_tr_b16 v[238:239], v162 offset:0x3600
	ds_read_b64_tr_b16 v[240:241], v162 offset:0x3e00
	s_waitcnt lgkmcnt(8)
	v_mfma_f32_32x32x16_bf16 v[32:47], v[166:169], v[182:185], v[32:47]
	v_exp_f32_e32 v80, v112
	v_exp_f32_e32 v81, v113
	v_mfma_f32_32x32x16_bf16 v[32:47], v[12:15], v[178:181], v[32:47]
	v_exp_f32_e32 v82, v114
	v_exp_f32_e32 v83, v115
	v_mfma_f32_32x32x16_bf16 v[32:47], v[8:11], v[174:177], v[32:47]
	v_exp_f32_e32 v84, v116
	v_exp_f32_e32 v85, v117
	v_mfma_f32_32x32x16_bf16 v[32:47], v[4:7], v[170:173], v[32:47]
	v_exp_f32_e32 v86, v118
	v_exp_f32_e32 v87, v119
	s_waitcnt lgkmcnt(0)
	v_mfma_f32_32x32x16_bf16 v[16:31], v[166:169], v[198:201], v[16:31]
	v_exp_f32_e32 v88, v120
	v_exp_f32_e32 v89, v121
	v_mfma_f32_32x32x16_bf16 v[16:31], v[12:15], v[230:233], v[16:31]
	v_exp_f32_e32 v90, v122
	v_exp_f32_e32 v91, v123
	v_mfma_f32_32x32x16_bf16 v[16:31], v[8:11], v[234:237], v[16:31]
	v_exp_f32_e32 v92, v124
	v_exp_f32_e32 v93, v125
	v_mfma_f32_32x32x16_bf16 v[16:31], v[4:7], v[238:241], v[16:31]
	v_exp_f32_e32 v94, v126
	v_exp_f32_e32 v95, v127
	v_cmp_gt_f32_e32 vcc, 1.0, v196
	s_cbranch_vccnz .Lresc_even_blk
